# P1 GEMM tile order: XM column blocks first, then XR, Y0a, Y0b (same permutation applied to the first tile in the prologue)
# speedup vs baseline: 1.0175x; 1.0166x over previous
; #define PG8_STAGE(bufoff, gbase, voff) do { _Pragma("unroll") for (int _i = 0; _i < 2; ++_i) \
;         __builtin_amdgcn_global_load_lds((const unsigned*)((const char*)(gbase) + (voff)[_i]), (PG8_LAS unsigned*)(lds + (bufoff) + ldsw + _i * 8192), 16, 0, 0); } while (0)
; #define PG8_WAIT_V(n) asm volatile("s_waitcnt vmcnt(" #n ")" ::: "memory")
; #define PG8_BAR __builtin_amdgcn_s_barrier()
; template <class Epi>
; __device__ __forceinline__ void gemm_phase(PG8_LAS unsigned char* lds, const Gemm g, const StaticOrder& S, const Epi& E) {
;     ...
;     const char* cA = (const char*)g.A + (size_t)cur.pm * tstep; const char* cB = (const char*)g.Bt + (size_t)cur.pn * tstep;
;     PG8_STAGE(PG8_SB(0, 0), cB, voffB); PG8_STAGE(PG8_SA(0, 0), cA, voffA); PG8_STAGE(PG8_SB(0, 1), cB + hstep, voffB); PG8_STAGE(PG8_SA(0, 1), cA + hstep, voffA);
;     if (wr == 1) PG8_BAR;
;     PG8_WAIT_V(4); PG8_BAR;
;     PG8_STAGE(PG8_SB(1, 0), cB + kstep, voffB); PG8_STAGE(PG8_SA(1, 0), cA + kstep, voffA); PG8_STAGE(PG8_SB(1, 1), cB + hstep + kstep, voffB);
;     PG8_WAIT_V(6); PG8_BAR;
.LBB0_44:
	s_add_i32 s5, s4, 16
	s_add_i32 s25, s4, -8
	s_cmp_lt_u32 s4, 8
	s_cselect_b32 s5, s5, s25
	s_cmp_lt_u32 s4, 24
	s_cselect_b32 s4, s5, s4
	s_andn2_b64 vcc, exec, s[2:3]
	s_cbranch_vccnz .LBB0_284
	v_lshrrev_b32_e32 v3, 1, v10
	v_and_b32_e32 v14, 24, v3
	v_lshrrev_b32_e32 v3, 5, v10
	v_and_b32_e32 v3, 4, v3
	v_bfe_u32 v4, v10, 2, 2
	v_lshlrev_b32_e32 v1, 4, v10
	v_and_b32_e32 v2, 32, v10
	v_bfe_u32 v13, v10, 2, 4
	v_or3_b32 v3, v3, v4, v14
	v_lshrrev_b32_e32 v4, 3, v10
	s_movk_i32 s3, 0x70
	v_bitop3_b32 v11, v1, v2, 48 bitop3:0x6c
	v_and_b32_e32 v12, 64, v10
	v_and_or_b32 v5, v4, s3, v13
	s_movk_i32 s3, 0x60
	v_add_u32_e32 v15, 0x2000, v1
	v_or_b32_e32 v2, v11, v12
	v_and_or_b32 v4, v4, s3, v3
	v_lshrrev_b32_e32 v1, 7, v15
	s_movk_i32 s3, 0xf0
	s_add_u32 s34, s64, 0x1c000000
	v_lshl_or_b32 v132, v4, 12, v2
	v_and_or_b32 v4, v1, s3, v13
	s_movk_i32 s3, 0xe0
	s_addc_u32 s35, s65, 0
	v_and_or_b32 v1, v1, s3, v3
	s_lshr_b32 s3, s33, 6
	s_ashr_i32 s25, s24, 31
	s_ashr_i32 s5, s4, 31
	s_lshr_b32 s2, s33, 8
	s_lshl_b32 s36, s3, 10
	s_waitcnt lgkmcnt(0)
	s_lshl_b64 s[6:7], s[24:25], 20
	s_lshl_b64 s[8:9], s[4:5], 20
	s_add_u32 s28, s34, s8
	s_addc_u32 s29, s35, s9
	s_add_i32 s37, s36, 0
	s_add_i32 m0, s37, 0x10000
	v_lshl_or_b32 v136, v1, 12, v2
	global_load_lds_dwordx4 v132, s[28:29]
	s_add_i32 m0, s37, 0x12000
	s_add_u32 s26, s64, s6
	v_lshl_or_b32 v130, v5, 12, v2
	global_load_lds_dwordx4 v136, s[28:29]
	s_addc_u32 s27, s65, s7
	s_mov_b32 m0, s37
	s_add_i32 s38, s37, 0x2000
	v_lshl_or_b32 v134, v4, 12, v2
	global_load_lds_dwordx4 v130, s[26:27]
	s_mov_b32 m0, s38
	s_add_u32 s6, s28, 0x80000
	global_load_lds_dwordx4 v134, s[26:27]
	s_addc_u32 s7, s29, 0
	s_add_i32 m0, s37, 0x14000
	v_mov_b32_e32 v139, 0
	global_load_lds_dwordx4 v132, s[6:7]
	s_add_i32 m0, s37, 0x16000
	v_mov_b32_e32 v133, v139
	global_load_lds_dwordx4 v136, s[6:7]
	s_add_u32 s6, s26, 0x80000
	s_addc_u32 s7, s27, 0
	s_add_i32 s39, s37, 0x4000
	s_mov_b32 m0, s39
	s_add_i32 s40, s37, 0x6000
	global_load_lds_dwordx4 v130, s[6:7]
	s_mov_b32 m0, s40
	v_mov_b32_e32 v137, v139
	global_load_lds_dwordx4 v134, s[6:7]
	v_mov_b32_e32 v131, v139
	v_mov_b32_e32 v135, v139
	s_mov_b32 s41, 0
	s_waitcnt vmcnt(0)
	v_lshl_add_u64 v[8:9], s[28:29], 0, v[132:133]
	v_lshl_add_u64 v[6:7], s[28:29], 0, v[136:137]
	v_lshl_add_u64 v[4:5], s[26:27], 0, v[130:131]
	s_cmp_lg_u32 s2, 1
	v_lshl_add_u64 v[2:3], s[26:27], 0, v[134:135]
	s_cbranch_scc1 .LBB0_47
	s_barrier

; template <class Epi>
; __device__ __forceinline__ void gemm_phase(PG8_LAS unsigned char* lds, const Gemm g, const StaticOrder& S, const Epi& E) {
;     ...
; #pragma unroll
;         for (int a = 0; a < 2; ++a)
; #pragma unroll
;             for (int b = 0; b < 2; ++b)
; #pragma unroll
;                 for (int m = 0; m < 4; ++m)
; #pragma unroll
;                     for (int n = 0; n < 2; ++n) acc[a][b][m][n] = (f32x4){0.f, 0.f, 0.f, 0.f};
;         cur = nxt; cA = nA; cB = nB; ++ui;
.LBB0_55:
	s_add_i32 s17, s16, 16
	s_add_i32 s19, s16, -8
	s_cmp_lt_u32 s16, 8
	s_cselect_b32 s17, s17, s19
	s_cmp_lt_u32 s16, 24
	s_cselect_b32 s16, s17, s16
	s_ashr_i32 s19, s18, 31
	v_cmp_lt_i64_e32 vcc, s[20:21], v[144:145]
	s_lshl_b64 s[20:21], s[18:19], 20
	s_add_u32 s20, s64, s20
	s_addc_u32 s21, s65, s21
	s_and_b64 s[22:23], vcc, exec
	s_cselect_b32 s5, s21, s27
	s_cselect_b32 s19, s20, s26
	s_ashr_i32 s17, s16, 31
	s_lshl_b64 s[22:23], s[16:17], 20
	s_add_u32 s22, s34, s22
	s_addc_u32 s23, s35, s23
	s_and_b64 s[30:31], vcc, exec
	s_cselect_b32 s17, s23, s29
	s_cselect_b32 s25, s22, s28
	s_add_u32 s26, s26, 0x80080
	s_addc_u32 s27, s27, 0
	s_add_u32 s48, s28, 0x100
	v_mov_b32_e32 v2, 0
	s_addc_u32 s49, s29, 0
	s_mov_b32 s50, -2
	v_mov_b32_e32 v3, v2
	v_mov_b32_e32 v4, v2
	v_mov_b32_e32 v5, v2
	v_mov_b32_e32 v6, v2
	v_mov_b32_e32 v7, v2
	v_mov_b32_e32 v8, v2
	v_mov_b32_e32 v9, v2
	v_mov_b32_e32 v18, v2
	v_mov_b32_e32 v19, v2
	v_mov_b32_e32 v20, v2
	v_mov_b32_e32 v21, v2
	v_mov_b32_e32 v22, v2
	v_mov_b32_e32 v23, v2
	v_mov_b32_e32 v24, v2
	v_mov_b32_e32 v25, v2
	v_mov_b32_e32 v34, v2
	v_mov_b32_e32 v35, v2
	v_mov_b32_e32 v36, v2
	v_mov_b32_e32 v37, v2
	v_mov_b32_e32 v38, v2
	v_mov_b32_e32 v39, v2
	v_mov_b32_e32 v40, v2
	v_mov_b32_e32 v41, v2
	v_mov_b32_e32 v50, v2
	v_mov_b32_e32 v51, v2
	v_mov_b32_e32 v52, v2
	v_mov_b32_e32 v53, v2
	v_mov_b32_e32 v54, v2
	v_mov_b32_e32 v55, v2
	v_mov_b32_e32 v56, v2
	v_mov_b32_e32 v57, v2
	v_mov_b32_e32 v10, v2
	v_mov_b32_e32 v11, v2
	v_mov_b32_e32 v12, v2
	v_mov_b32_e32 v13, v2
	v_mov_b32_e32 v14, v2
	v_mov_b32_e32 v15, v2
	v_mov_b32_e32 v16, v2
	v_mov_b32_e32 v17, v2
	v_mov_b32_e32 v26, v2
	v_mov_b32_e32 v27, v2
	v_mov_b32_e32 v28, v2
	v_mov_b32_e32 v29, v2
	v_mov_b32_e32 v30, v2
	v_mov_b32_e32 v31, v2
	v_mov_b32_e32 v32, v2
	v_mov_b32_e32 v33, v2
	v_mov_b32_e32 v42, v2
	v_mov_b32_e32 v43, v2
	v_mov_b32_e32 v44, v2
	v_mov_b32_e32 v45, v2
	v_mov_b32_e32 v46, v2
	v_mov_b32_e32 v47, v2
	v_mov_b32_e32 v48, v2
	v_mov_b32_e32 v49, v2
	v_mov_b32_e32 v58, v2
	v_mov_b32_e32 v59, v2
	v_mov_b32_e32 v60, v2
	v_mov_b32_e32 v61, v2
	v_mov_b32_e32 v62, v2
	v_mov_b32_e32 v63, v2
	v_mov_b32_e32 v64, v2
	v_mov_b32_e32 v65, v2
	v_mov_b32_e32 v66, v2
	v_mov_b32_e32 v67, v2
	v_mov_b32_e32 v68, v2
	v_mov_b32_e32 v69, v2
	v_mov_b32_e32 v70, v2
	v_mov_b32_e32 v71, v2
	v_mov_b32_e32 v72, v2
	v_mov_b32_e32 v73, v2
	v_mov_b32_e32 v82, v2
	v_mov_b32_e32 v83, v2
	v_mov_b32_e32 v84, v2
	v_mov_b32_e32 v85, v2
	v_mov_b32_e32 v86, v2
	v_mov_b32_e32 v87, v2
	v_mov_b32_e32 v88, v2
	v_mov_b32_e32 v89, v2
	v_mov_b32_e32 v98, v2
	v_mov_b32_e32 v99, v2
	v_mov_b32_e32 v100, v2
	v_mov_b32_e32 v101, v2
	v_mov_b32_e32 v102, v2
	v_mov_b32_e32 v103, v2
	v_mov_b32_e32 v104, v2
	v_mov_b32_e32 v105, v2
	v_mov_b32_e32 v114, v2
	v_mov_b32_e32 v115, v2
	v_mov_b32_e32 v116, v2
	v_mov_b32_e32 v117, v2
	v_mov_b32_e32 v118, v2
	v_mov_b32_e32 v119, v2
	v_mov_b32_e32 v120, v2
	v_mov_b32_e32 v121, v2
	v_mov_b32_e32 v74, v2
	v_mov_b32_e32 v75, v2
	v_mov_b32_e32 v76, v2
	v_mov_b32_e32 v77, v2
	v_mov_b32_e32 v78, v2
	v_mov_b32_e32 v79, v2
	v_mov_b32_e32 v80, v2
	v_mov_b32_e32 v81, v2
	v_mov_b32_e32 v90, v2
	v_mov_b32_e32 v91, v2
	v_mov_b32_e32 v92, v2
	v_mov_b32_e32 v93, v2
	v_mov_b32_e32 v94, v2
	v_mov_b32_e32 v95, v2
	v_mov_b32_e32 v96, v2
	v_mov_b32_e32 v97, v2
	v_mov_b32_e32 v106, v2
	v_mov_b32_e32 v107, v2
	v_mov_b32_e32 v108, v2
	v_mov_b32_e32 v109, v2
	v_mov_b32_e32 v110, v2
	v_mov_b32_e32 v111, v2
	v_mov_b32_e32 v112, v2
	v_mov_b32_e32 v113, v2
	v_mov_b32_e32 v122, v2
	v_mov_b32_e32 v123, v2
	v_mov_b32_e32 v124, v2
	v_mov_b32_e32 v125, v2
	v_mov_b32_e32 v126, v2
	v_mov_b32_e32 v127, v2
	v_mov_b32_e32 v128, v2
	v_mov_b32_e32 v129, v2
